# HGRN2 blocks leave the mixers phase after their scan (attention tasks go to the other blocks)
# speedup vs baseline: 1.0801x; 1.0007x over previous
; __device__ __forceinline__ int otid() { int t = threadIdx.x; asm volatile("" : "+v"(t)); return t; }
; __device__ __forceinline__ void phase_mixers(const Params& p, int l, char* smem, bool scans_only) {
;     ...
;   for (int it = 0;; ++it) {
;     int t;
;     if (it == 0 && first >= 0) t = first;
;     else {
;       if (otid() == 0) *s_taskp = atomicAdd(ctr, 1) + (full ? n_scan : 0);
;       __syncthreads();
;       t = *s_taskp;
;       __syncthreads();
;     }
;     if (t >= total) break;
;     if (t < n_dn) dn_task(p, l, t, smem);
;     else if (t < n_dn + n_hg) hg_task(p, l, t - n_dn, smem);
;     else if (t < n_scan) s5_task(p, l, t - n_dn - n_hg, smem);
;     else { const bool ic = t >= n_scan + n_al; attn_task(p, l, t - n_scan - (ic ? n_al : 0), ic, smem); }
;     __syncthreads();
;   }
.LBB0_109:
	s_cmpk_lt_u32 s2, 0x100
	s_cbranch_scc1 .Lhg_go
	s_cmpk_lt_u32 s2, 0x180
	s_cbranch_scc0 .Lhg_go
	s_mov_b64 s[40:41], -1
	s_branch .LBB0_106
